# passA chunk loop: the per-step zeroing of the ones-column operand for lanes fr != 0 removed (those accumulator columns are never stored)
# baseline (speedup 1.0000x reference)
; #define LAS __attribute__((address_space(3)))
; __device__ void passA(const Params& p, LAS unsigned char* lds, int wg) {
;     ...
;         for (int a = 0; a < 2; ++a) { nacc[a] *= decay;
; #pragma unroll
;             for (int v = 0; v < 4; ++v) acc[a][v] *= decay; }
; #pragma unroll
;         for (int ks = 0; ks < 4; ++ks) { bf16x8 kf[2], vf[4];
; #pragma unroll
;             for (int kt = 0; kt < 2; ++kt) kf[kt] = *(const LAS bf16x8*)(Kt + (wid * 32 + 8 * (fr >> 2) + 4 * kt + (fr & 3)) * 136 + ks * 32 + fq * 8);
; #pragma unroll
;             for (int vt = 0; vt < 4; ++vt) vf[vt] = *(const LAS bf16x8*)(Ve + (vt * 16 + fr) * 136 + ks * 32 + fq * 8);
;             bf16x8 ef = *(const LAS bf16x8*)(eB + st * 128 + ks * 32 + fq * 8);
;             if (fr != 0) ef = (bf16x8){0, 0, 0, 0, 0, 0, 0, 0};
; #pragma unroll
;             for (int kt = 0; kt < 2; ++kt) {
; #pragma unroll
;                 for (int vt = 0; vt < 4; ++vt) acc[kt][vt] = __builtin_amdgcn_mfma_f32_16x16x32_bf16(kf[kt], vf[vt], acc[kt][vt], 0, 0, 0);
;                 nacc[kt] = __builtin_amdgcn_mfma_f32_16x16x32_bf16(kf[kt], ef, nacc[kt], 0, 0, 0); } }
.LBB0_391:
	ds_read_b128 v[114:117], v110
	ds_read_b128 v[118:121], v111
	v_add_u32_e32 v113, 0, v105
	v_add_u32_e32 v126, 0x17c80, v113
	ds_read_b128 v[122:125], v111 offset:4352
	ds_read_b128 v[126:129], v126
	ds_read_b128 v[130:133], v110 offset:64
	ds_read_b128 v[134:137], v111 offset:8704
	ds_read_b128 v[138:141], v111 offset:192
	ds_read_b128 v[142:145], v111 offset:13056
	ds_read_b128 v[146:149], v111 offset:4544
	ds_read_b128 v[150:153], v110 offset:1088
	v_pk_mul_f32 v[78:79], v[78:79], v[82:83] op_sel_hi:[1,0]
	v_pk_mul_f32 v[76:77], v[76:77], v[82:83] op_sel_hi:[1,0]
	v_pk_mul_f32 v[74:75], v[74:75], v[82:83] op_sel_hi:[1,0]
	v_pk_mul_f32 v[72:73], v[72:73], v[82:83] op_sel_hi:[1,0]
	v_pk_mul_f32 v[70:71], v[70:71], v[82:83] op_sel_hi:[1,0]
	v_pk_mul_f32 v[68:69], v[68:69], v[82:83] op_sel_hi:[1,0]
	v_pk_mul_f32 v[66:67], v[66:67], v[82:83] op_sel_hi:[1,0]
	v_pk_mul_f32 v[64:65], v[64:65], v[82:83] op_sel_hi:[1,0]
	v_pk_mul_f32 v[42:43], v[42:43], v[82:83] op_sel_hi:[1,0]
	v_pk_mul_f32 v[40:41], v[40:41], v[82:83] op_sel_hi:[1,0]
	s_waitcnt lgkmcnt(6)
	v_mfma_f32_16x16x32_bf16 v[72:75], v[114:117], v[118:121], v[72:75]
	v_mul_f32_e64 v46, v46, v82
	v_mul_f32_e64 v47, v47, v82
	v_pk_mul_f32 v[44:45], v[44:45], v[82:83] op_sel_hi:[1,0]
	v_pk_mul_f32 v[50:51], v[50:51], v[82:83] op_sel_hi:[1,0]
	v_mfma_f32_16x16x32_bf16 v[68:71], v[114:117], v[122:125], v[68:71]
	v_mul_f32_e64 v48, v48, v82
	v_mul_f32_e64 v49, v49, v82
	v_pk_mul_f32 v[54:55], v[54:55], v[82:83] op_sel_hi:[1,0]
	v_pk_mul_f32 v[52:53], v[52:53], v[82:83] op_sel_hi:[1,0]
	s_waitcnt lgkmcnt(4)
	v_mfma_f32_16x16x32_bf16 v[64:67], v[114:117], v[134:137], v[64:67]
	v_mul_f32_e64 v62, v62, v82
	v_mul_f32_e64 v63, v63, v82
	v_pk_mul_f32 v[60:61], v[60:61], v[82:83] op_sel_hi:[1,0]
	ds_read_b128 v[154:157], v111 offset:8896
	s_waitcnt lgkmcnt(3)
	v_mfma_f32_16x16x32_bf16 v[40:43], v[114:117], v[142:145], v[40:43]
	v_mul_f32_e64 v58, v58, v82
	v_mul_f32_e64 v59, v59, v82
	v_pk_mul_f32 v[56:57], v[56:57], v[82:83] op_sel_hi:[1,0]
	v_add_u32_e32 v82, 0x17cc0, v113
	v_mfma_f32_16x16x32_bf16 v[76:79], v[114:117], v[126:129], v[76:79]
	ds_read_b128 v[114:117], v110 offset:1152
	s_add_i32 s27, s27, 1
	s_add_i32 s28, s28, -1
	s_waitcnt lgkmcnt(2)
	v_mfma_f32_16x16x32_bf16 v[44:47], v[150:153], v[118:121], v[44:47]
	v_add_u32_e32 v105, 0x100, v105
	v_add_u32_e32 v112, 0x200, v112
	s_add_i32 s40, s40, 4
	v_mfma_f32_16x16x32_bf16 v[48:51], v[150:153], v[122:125], v[48:51]
	v_mfma_f32_16x16x32_bf16 v[52:55], v[150:153], v[134:137], v[52:55]
	v_mfma_f32_16x16x32_bf16 v[60:63], v[150:153], v[126:129], v[60:63]
	ds_read_b128 v[118:121], v111 offset:64
	ds_read_b128 v[122:125], v111 offset:4416
	ds_read_b128 v[126:129], v111 offset:128
	ds_read_b128 v[134:137], v111 offset:8768
	v_mfma_f32_16x16x32_bf16 v[56:59], v[150:153], v[142:145], v[56:59]
	ds_read_b128 v[142:145], v111 offset:4480
	ds_read_b128 v[150:153], v82
	ds_read_b128 v[160:163], v111 offset:13120
	ds_read_b128 v[164:167], v111 offset:8832
	v_add_u32_e32 v82, 0x17d00, v113
	s_waitcnt lgkmcnt(7)
	v_mfma_f32_16x16x32_bf16 v[72:75], v[130:133], v[118:121], v[72:75]
	s_waitcnt lgkmcnt(2)
	v_mfma_f32_16x16x32_bf16 v[68:71], v[130:133], v[122:125], v[68:71]
	ds_read_b128 v[168:171], v111 offset:13248
	ds_read_b128 v[172:175], v111 offset:13184
	v_mfma_f32_16x16x32_bf16 v[44:47], v[114:117], v[118:121], v[44:47]
	v_mfma_f32_16x16x32_bf16 v[48:51], v[114:117], v[122:125], v[48:51]
	v_mfma_f32_16x16x32_bf16 v[52:55], v[114:117], v[134:137], v[52:55]
	s_waitcnt lgkmcnt(3)
	v_mfma_f32_16x16x32_bf16 v[56:59], v[114:117], v[160:163], v[56:59]
	v_mfma_f32_16x16x32_bf16 v[60:63], v[114:117], v[150:153], v[60:63]
	ds_read_b128 v[114:117], v110 offset:128
	ds_read_b128 v[118:121], v110 offset:192
	ds_read_b128 v[122:125], v82
	v_add_u32_e32 v82, 0x17d40, v113
	v_mfma_f32_16x16x32_bf16 v[64:67], v[130:133], v[134:137], v[64:67]
	s_waitcnt lgkmcnt(0)
	v_mfma_f32_16x16x32_bf16 v[40:43], v[130:133], v[160:163], v[40:43]
	v_mfma_f32_16x16x32_bf16 v[76:79], v[130:133], v[150:153], v[76:79]
	ds_read_b128 v[130:133], v82
	v_mfma_f32_16x16x32_bf16 v[72:75], v[114:117], v[126:129], v[72:75]
	v_mfma_f32_16x16x32_bf16 v[68:71], v[114:117], v[142:145], v[68:71]
	v_mfma_f32_16x16x32_bf16 v[64:67], v[114:117], v[164:167], v[64:67]
	v_mfma_f32_16x16x32_bf16 v[40:43], v[114:117], v[172:175], v[40:43]
	v_mfma_f32_16x16x32_bf16 v[76:79], v[114:117], v[122:125], v[76:79]
	ds_read_b128 v[114:117], v110 offset:1216
	ds_read_b128 v[134:137], v110 offset:1280
	s_waitcnt lgkmcnt(0)
	s_barrier
	v_mfma_f32_16x16x32_bf16 v[44:47], v[114:117], v[126:129], v[44:47]
	v_mfma_f32_16x16x32_bf16 v[48:51], v[114:117], v[142:145], v[48:51]
	v_mfma_f32_16x16x32_bf16 v[52:55], v[114:117], v[164:167], v[52:55]
	v_mfma_f32_16x16x32_bf16 v[56:59], v[114:117], v[172:175], v[56:59]
	v_mfma_f32_16x16x32_bf16 v[60:63], v[114:117], v[122:125], v[60:63]
	v_mfma_f32_16x16x32_bf16 v[72:75], v[118:121], v[138:141], v[72:75]
	v_mfma_f32_16x16x32_bf16 v[68:71], v[118:121], v[146:149], v[68:71]
	v_mfma_f32_16x16x32_bf16 v[64:67], v[118:121], v[154:157], v[64:67]
	v_mfma_f32_16x16x32_bf16 v[40:43], v[118:121], v[168:171], v[40:43]
	v_mfma_f32_16x16x32_bf16 v[76:79], v[118:121], v[130:133], v[76:79]
	v_mfma_f32_16x16x32_bf16 v[44:47], v[134:137], v[138:141], v[44:47]
	v_mfma_f32_16x16x32_bf16 v[48:51], v[134:137], v[146:149], v[48:51]
	v_mfma_f32_16x16x32_bf16 v[52:55], v[134:137], v[154:157], v[52:55]
	v_mfma_f32_16x16x32_bf16 v[56:59], v[134:137], v[168:171], v[56:59]
	v_mfma_f32_16x16x32_bf16 v[60:63], v[134:137], v[130:133], v[60:63]
